# stack5 + attention steady loops: LDS-DMA issue blocks slimmed (no m0 save/restore; in the diff loop the SALU writes m0 directly and the address add fills the wait state): 24 fewer instructions per two
# speedup vs baseline: 1.0035x; 1.0035x over previous
.LBB0_251:
	v_add_u32_e32 v0, s18, v225
	ds_read_b64_tr_b16 v[192:193], v0 offset:24576
	ds_read_b64_tr_b16 v[194:195], v0 offset:25088
	v_add_f32_e32 v2, v80, v81
	v_add_f32_e32 v2, v82, v2
	v_add_f32_e32 v2, v83, v2
	v_add_f32_e32 v2, v84, v2
	v_add_f32_e32 v2, v85, v2
	v_cvt_pk_bf16_f32 v156, v80, v81
	v_cvt_pk_bf16_f32 v157, v82, v83
	s_waitcnt lgkmcnt(9)
	v_mfma_f32_32x32x16_bf16 v[96:111], v[188:191], v[140:143], v[48:63]
	ds_read_b64_tr_b16 v[188:189], v0 offset:28672
	ds_read_b64_tr_b16 v[190:191], v0 offset:29184
	v_add_f32_e32 v2, v86, v2
	v_add_f32_e32 v2, v87, v2
	v_add_f32_e32 v2, v88, v2
	v_add_f32_e32 v2, v89, v2
	v_cvt_pk_bf16_f32 v158, v84, v85
	v_cvt_pk_bf16_f32 v159, v86, v87
	s_waitcnt lgkmcnt(10)
	v_mfma_f32_32x32x16_bf16 v[112:127], v[184:187], v[140:143], v[48:63]
	ds_read_b64_tr_b16 v[10:11], v0 offset:25600
	ds_read_b64_tr_b16 v[12:13], v0 offset:26112
	v_add_f32_e32 v2, v90, v2
	v_add_f32_e32 v2, v91, v2
	v_add_f32_e32 v2, v92, v2
	v_add_f32_e32 v2, v93, v2
	v_cvt_pk_bf16_f32 v152, v88, v89
	v_cvt_pk_bf16_f32 v153, v90, v91
	s_waitcnt lgkmcnt(11)
	v_mfma_f32_32x32x16_bf16 v[96:111], v[180:183], v[136:139], v[96:111]
	ds_read_b64_tr_b16 v[180:181], v0 offset:29696
	ds_read_b64_tr_b16 v[182:183], v0 offset:30208
	v_add_f32_e32 v2, v94, v2
	v_add_f32_e32 v2, v95, v2
	v_add_f32_e32 v2, v64, v2
	v_add_f32_e32 v2, v65, v2
	v_cvt_pk_bf16_f32 v154, v92, v93
	v_cvt_pk_bf16_f32 v155, v94, v95
	s_waitcnt lgkmcnt(12)
	v_mfma_f32_32x32x16_bf16 v[112:127], v[176:179], v[136:139], v[112:127]
	ds_read_b64_tr_b16 v[176:177], v0 offset:26624
	ds_read_b64_tr_b16 v[178:179], v0 offset:27136
	v_add_f32_e32 v2, v66, v2
	v_add_f32_e32 v2, v67, v2
	v_add_f32_e32 v2, v68, v2
	v_add_f32_e32 v6, v69, v2
	v_cvt_pk_bf16_f32 v148, v64, v65
	v_cvt_pk_bf16_f32 v149, v66, v67
	s_waitcnt lgkmcnt(13)
	v_mfma_f32_32x32x16_bf16 v[96:111], v[172:175], v[132:135], v[96:111]
	ds_read_b64_tr_b16 v[2:3], v0 offset:30720
	ds_read_b64_tr_b16 v[4:5], v0 offset:31232
	v_add_f32_e32 v6, v70, v6
	v_add_f32_e32 v6, v71, v6
	v_add_f32_e32 v6, v72, v6
	v_add_f32_e32 v14, v73, v6
	v_cvt_pk_bf16_f32 v150, v68, v69
	v_cvt_pk_bf16_f32 v151, v70, v71
	s_waitcnt lgkmcnt(14)
	v_mfma_f32_32x32x16_bf16 v[112:127], v[168:171], v[132:135], v[112:127]
	ds_read_b64_tr_b16 v[6:7], v0 offset:27648
	ds_read_b64_tr_b16 v[8:9], v0 offset:28160
	v_add_f32_e32 v14, v74, v14
	v_add_f32_e32 v14, v75, v14
	v_add_f32_e32 v14, v76, v14
	v_add_f32_e32 v14, v77, v14
	v_cvt_pk_bf16_f32 v144, v72, v73
	v_cvt_pk_bf16_f32 v145, v74, v75
	s_waitcnt lgkmcnt(14)
	v_mfma_f32_32x32x16_bf16 v[96:111], v[164:167], v[128:131], v[96:111]
	ds_read_b64_tr_b16 v[164:165], v0 offset:31744
	ds_read_b64_tr_b16 v[166:167], v0 offset:32256
	v_add_f32_e32 v0, v78, v14
	v_add_f32_e32 v0, v79, v0
	v_add_f32_e32 v0, 0, v0
	v_cvt_pk_bf16_f32 v146, v76, v77
	v_cvt_pk_bf16_f32 v147, v78, v79
	v_mfma_f32_32x32x16_bf16 v[112:127], v[160:163], v[128:131], v[112:127]
	v_lshl_add_u64 v[14:15], v[202:203], 0, s[54:55]
	s_add_i32 s18, s69, s38
	s_mov_b32 m0, s18
	s_nop 0
	global_load_lds_dwordx4 v[14:15], off
	v_lshl_add_u64 v[14:15], v[200:201], 0, s[54:55]
	s_add_i32 s18, s7, s59
	s_mov_b32 m0, s18
	s_nop 0
	global_load_lds_dwordx4 v[14:15], off
	ds_read_b128 v[64:67], v204
	ds_read_b128 v[68:71], v204 offset:32
	ds_read_b128 v[72:75], v204 offset:128
	v_add_f32_e32 v0, v230, v0
	s_waitcnt lgkmcnt(2)
	v_pk_add_f32 v[82:83], v[98:99], v[66:67]
	s_waitcnt lgkmcnt(1)
	v_pk_add_f32 v[84:85], v[100:101], v[68:69]
	s_waitcnt lgkmcnt(0)
	v_pk_add_f32 v[14:15], v[112:113], v[72:73]
	v_pk_add_f32 v[66:67], v[114:115], v[74:75]
	ds_read_b128 v[72:75], v204 offset:160
	v_pk_add_f32 v[86:87], v[102:103], v[70:71]
	v_pk_add_f32 v[64:65], v[96:97], v[64:65]
	v_max3_f32 v81, v82, v83, v15
	v_max_f32_e32 v80, v64, v65
	s_waitcnt lgkmcnt(0)
	v_pk_add_f32 v[68:69], v[116:117], v[72:73]
	v_pk_add_f32 v[70:71], v[118:119], v[74:75]
	ds_read_b128 v[72:75], v204 offset:64
	ds_read_b128 v[76:79], v204 offset:192
	v_max3_f32 v80, v80, v14, v66
	v_max3_f32 v80, v80, v67, v84
	v_max3_f32 v81, v81, v86, v87
	s_waitcnt lgkmcnt(1)
	v_pk_add_f32 v[88:89], v[104:105], v[72:73]
	s_waitcnt lgkmcnt(0)
	v_pk_add_f32 v[72:73], v[120:121], v[76:77]
	v_pk_add_f32 v[90:91], v[106:107], v[74:75]
	v_pk_add_f32 v[74:75], v[122:123], v[78:79]
	ds_read_b128 v[76:79], v204 offset:96
	ds_read_b128 v[94:97], v204 offset:224
	v_max3_f32 v80, v80, v85, v68
	v_max3_f32 v81, v81, v70, v71
	v_max3_f32 v80, v80, v69, v88
	v_max3_f32 v81, v81, v90, v91
	s_waitcnt lgkmcnt(1)
	v_pk_add_f32 v[92:93], v[108:109], v[76:77]
	s_waitcnt lgkmcnt(0)
	v_pk_add_f32 v[76:77], v[124:125], v[94:95]
	v_pk_add_f32 v[94:95], v[110:111], v[78:79]
	v_max3_f32 v80, v80, v89, v72
	v_max3_f32 v81, v81, v74, v75
	v_pk_add_f32 v[78:79], v[126:127], v[96:97]
	v_max3_f32 v80, v80, v73, v92
	v_max3_f32 v81, v81, v94, v95
	v_max3_f32 v80, v80, v93, v76
	v_max3_f32 v81, v81, v78, v79
	v_max3_f32 v80, v80, v77, v81
	v_mov_b32_e32 v81, v80
	s_nop 1
	v_permlane32_swap_b32_e32 v80, v81
	v_max_f32_e32 v81, v81, v81
	v_max_f32_e32 v80, v80, v80
	v_max_f32_e32 v80, v80, v81
	v_cmp_lt_f32_e32 vcc, s96, v80
	s_cmp_lg_u64 vcc, 0
	s_cselect_b64 s[18:19], -1, 0
	s_cbranch_vccnz .LBB0_259

.LBB0_254:
	s_add_i32 s18, s7, 0x2000
	s_cmpk_lg_i32 s7, 0x4000
	s_cselect_b32 s60, s18, 0
	v_add_u32_e32 v14, s69, v225
	ds_read_b64_tr_b16 v[168:169], v14 offset:24576
	ds_read_b64_tr_b16 v[170:171], v14 offset:25088
	v_add_f32_e32 v2, v80, v81
	v_add_f32_e32 v2, v82, v2
	v_add_f32_e32 v2, v83, v2
	v_add_f32_e32 v2, v84, v2
	v_add_f32_e32 v2, v85, v2
	v_cvt_pk_bf16_f32 v156, v80, v81
	v_cvt_pk_bf16_f32 v157, v82, v83
	s_waitcnt lgkmcnt(9)
	v_mfma_f32_32x32x16_bf16 v[96:111], v[112:115], v[140:143], v[48:63]
	ds_read_b64_tr_b16 v[164:165], v14 offset:28672
	ds_read_b64_tr_b16 v[166:167], v14 offset:29184
	v_add_f32_e32 v2, v86, v2
	v_add_f32_e32 v2, v87, v2
	v_add_f32_e32 v2, v88, v2
	v_add_f32_e32 v2, v89, v2
	v_cvt_pk_bf16_f32 v158, v84, v85
	v_cvt_pk_bf16_f32 v159, v86, v87
	s_waitcnt lgkmcnt(10)
	v_mfma_f32_32x32x16_bf16 v[112:127], v[160:163], v[140:143], v[48:63]
	ds_read_b64_tr_b16 v[10:11], v14 offset:25600
	ds_read_b64_tr_b16 v[12:13], v14 offset:26112
	v_add_f32_e32 v2, v90, v2
	v_add_f32_e32 v2, v91, v2
	v_add_f32_e32 v2, v92, v2
	v_add_f32_e32 v2, v93, v2
	v_cvt_pk_bf16_f32 v152, v88, v89
	v_cvt_pk_bf16_f32 v153, v90, v91
	s_waitcnt lgkmcnt(11)
	v_mfma_f32_32x32x16_bf16 v[96:111], v[192:195], v[136:139], v[96:111]
	ds_read_b64_tr_b16 v[160:161], v14 offset:29696
	ds_read_b64_tr_b16 v[162:163], v14 offset:30208
	v_add_f32_e32 v2, v94, v2
	v_add_f32_e32 v2, v95, v2
	v_add_f32_e32 v2, v64, v2
	v_add_f32_e32 v2, v65, v2
	v_cvt_pk_bf16_f32 v154, v92, v93
	v_cvt_pk_bf16_f32 v155, v94, v95
	s_waitcnt lgkmcnt(12)
	v_mfma_f32_32x32x16_bf16 v[112:127], v[188:191], v[136:139], v[112:127]
	ds_read_b64_tr_b16 v[196:197], v14 offset:26624
	ds_read_b64_tr_b16 v[198:199], v14 offset:27136
	v_add_f32_e32 v2, v66, v2
	v_add_f32_e32 v2, v67, v2
	v_add_f32_e32 v2, v68, v2
	v_add_f32_e32 v6, v69, v2
	v_cvt_pk_bf16_f32 v148, v64, v65
	v_cvt_pk_bf16_f32 v149, v66, v67
	s_waitcnt lgkmcnt(13)
	v_mfma_f32_32x32x16_bf16 v[96:111], v[184:187], v[132:135], v[96:111]
	ds_read_b64_tr_b16 v[2:3], v14 offset:30720
	ds_read_b64_tr_b16 v[4:5], v14 offset:31232
	v_add_f32_e32 v6, v70, v6
	v_add_f32_e32 v6, v71, v6
	v_add_f32_e32 v6, v72, v6
	v_add_f32_e32 v15, v73, v6
	v_cvt_pk_bf16_f32 v150, v68, v69
	v_cvt_pk_bf16_f32 v151, v70, v71
	s_waitcnt lgkmcnt(14)
	v_mfma_f32_32x32x16_bf16 v[112:127], v[180:183], v[132:135], v[112:127]
	ds_read_b64_tr_b16 v[6:7], v14 offset:27648
	ds_read_b64_tr_b16 v[8:9], v14 offset:28160
	v_add_f32_e32 v15, v74, v15
	v_add_f32_e32 v15, v75, v15
	v_add_f32_e32 v15, v76, v15
	v_add_f32_e32 v15, v77, v15
	v_cvt_pk_bf16_f32 v144, v72, v73
	v_cvt_pk_bf16_f32 v145, v74, v75
	s_waitcnt lgkmcnt(14)
	v_mfma_f32_32x32x16_bf16 v[96:111], v[176:179], v[128:131], v[96:111]
	ds_read_b64_tr_b16 v[192:193], v14 offset:31744
	ds_read_b64_tr_b16 v[194:195], v14 offset:32256
	v_add_f32_e32 v14, v78, v15
	v_add_f32_e32 v14, v79, v14
	v_add_f32_e32 v80, 0, v14
	v_cvt_pk_bf16_f32 v146, v76, v77
	v_cvt_pk_bf16_f32 v147, v78, v79
	v_mfma_f32_32x32x16_bf16 v[112:127], v[172:175], v[128:131], v[112:127]
	s_add_i32 s18, s7, s38
	s_mov_b32 m0, s18
	s_nop 0
	global_load_lds_dwordx4 v[202:203], off
	s_add_i32 s18, s60, s59
	s_mov_b32 m0, s18
	s_nop 0
	global_load_lds_dwordx4 v[200:201], off
	ds_read_b128 v[64:67], v204 offset:256
	ds_read_b128 v[68:71], v204 offset:288
	ds_read_b128 v[72:75], v204 offset:384
	v_add_f32_e32 v230, v0, v80
	s_waitcnt lgkmcnt(2)
	v_pk_add_f32 v[82:83], v[98:99], v[66:67]
	s_waitcnt lgkmcnt(1)
	v_pk_add_f32 v[84:85], v[100:101], v[68:69]
	s_waitcnt lgkmcnt(0)
	s_nop 0
	v_pk_add_f32 v[14:15], v[112:113], v[72:73]
	v_pk_add_f32 v[66:67], v[114:115], v[74:75]
	ds_read_b128 v[72:75], v204 offset:416
	v_pk_add_f32 v[86:87], v[102:103], v[70:71]
	v_pk_add_f32 v[64:65], v[96:97], v[64:65]
	s_waitcnt lgkmcnt(0)
	v_pk_add_f32 v[68:69], v[116:117], v[72:73]
	v_pk_add_f32 v[70:71], v[118:119], v[74:75]
	ds_read_b128 v[72:75], v204 offset:320
	ds_read_b128 v[76:79], v204 offset:448
	v_max_f32_e32 v81, v64, v65
	v_max3_f32 v81, v81, v14, v66
	v_max3_f32 v81, v81, v67, v84
	s_waitcnt lgkmcnt(1)
	v_pk_add_f32 v[88:89], v[104:105], v[72:73]
	s_waitcnt lgkmcnt(0)
	v_pk_add_f32 v[72:73], v[120:121], v[76:77]
	v_pk_add_f32 v[90:91], v[106:107], v[74:75]
	v_pk_add_f32 v[74:75], v[122:123], v[78:79]
	ds_read_b128 v[76:79], v204 offset:352
	ds_read_b128 v[94:97], v204 offset:480
	v_max3_f32 v81, v81, v85, v68
	v_max3_f32 v81, v81, v69, v88
	v_max3_f32 v81, v81, v89, v72
	s_waitcnt lgkmcnt(1)
	v_pk_add_f32 v[92:93], v[108:109], v[76:77]
	s_waitcnt lgkmcnt(0)
	v_pk_add_f32 v[76:77], v[124:125], v[94:95]
	v_pk_add_f32 v[94:95], v[110:111], v[78:79]
	v_pk_add_f32 v[78:79], v[126:127], v[96:97]
	v_max3_f32 v96, v82, v83, v15
	v_max3_f32 v96, v96, v86, v87
	v_max3_f32 v96, v96, v70, v71
	v_max3_f32 v96, v96, v90, v91
	v_max3_f32 v96, v96, v74, v75
	v_max3_f32 v81, v81, v73, v92
	v_max3_f32 v96, v96, v94, v95
	v_max3_f32 v81, v81, v93, v76
	v_max3_f32 v96, v96, v78, v79
	v_max3_f32 v0, v81, v77, v96
	v_mov_b32_e32 v80, v0
	s_nop 1
	v_permlane32_swap_b32_e32 v0, v80
	v_max_f32_e32 v80, v80, v80
	v_max_f32_e32 v0, v0, v0
	v_max_f32_e32 v0, v0, v80
	v_cmp_lt_f32_e32 vcc, s96, v0
	s_cmp_lg_u64 vcc, 0
	s_cselect_b64 s[18:19], -1, 0
	s_cbranch_vccnz .LBB0_262

.LBB0_280:
	s_waitcnt lgkmcnt(7)
	v_mfma_f32_32x32x16_bf16 v[144:159], v[220:223], v[184:187], v[80:95]
	v_add_f32_e32 v2, v112, v113
	v_add_f32_e32 v2, v114, v2
	v_add_f32_e32 v2, v115, v2
	s_lshl_b32 s72, s72, 1
	v_add_f32_e32 v2, v116, v2
	v_add_u32_e32 v0, s72, v245
	v_add_f32_e32 v2, v117, v2
	v_cvt_pk_bf16_f32 v188, v112, v113
	v_cvt_pk_bf16_f32 v189, v114, v115
	s_waitcnt lgkmcnt(6)
	v_mfma_f32_32x32x16_bf16 v[128:143], v[212:215], v[184:187], v[80:95]
	v_add_f32_e32 v2, v118, v2
	v_add_f32_e32 v2, v119, v2
	v_add_f32_e32 v2, v120, v2
	v_add_f32_e32 v2, v121, v2
	v_cvt_pk_bf16_f32 v190, v116, v117
	v_cvt_pk_bf16_f32 v191, v118, v119
	s_waitcnt lgkmcnt(5)
	v_mfma_f32_32x32x16_bf16 v[144:159], v[216:219], v[176:179], v[144:159]
	v_add_f32_e32 v2, v122, v2
	v_add_f32_e32 v2, v123, v2
	v_add_f32_e32 v2, v124, v2
	v_add_f32_e32 v2, v125, v2
	v_cvt_pk_bf16_f32 v180, v120, v121
	v_cvt_pk_bf16_f32 v181, v122, v123
	s_waitcnt lgkmcnt(4)
	v_mfma_f32_32x32x16_bf16 v[128:143], v[204:207], v[176:179], v[128:143]
	v_add_f32_e32 v2, v126, v2
	v_add_f32_e32 v2, v127, v2
	v_add_f32_e32 v2, v96, v2
	v_add_f32_e32 v2, v97, v2
	v_cvt_pk_bf16_f32 v182, v124, v125
	v_cvt_pk_bf16_f32 v183, v126, v127
	s_waitcnt lgkmcnt(3)
	v_mfma_f32_32x32x16_bf16 v[144:159], v[208:211], v[172:175], v[144:159]
	v_add_f32_e32 v2, v98, v2
	v_add_f32_e32 v2, v99, v2
	v_add_f32_e32 v2, v100, v2
	v_add_f32_e32 v2, v101, v2
	v_cvt_pk_bf16_f32 v168, v96, v97
	v_cvt_pk_bf16_f32 v169, v98, v99
	s_waitcnt lgkmcnt(2)
	v_mfma_f32_32x32x16_bf16 v[128:143], v[200:203], v[172:175], v[128:143]
	v_add_f32_e32 v2, v102, v2
	v_add_f32_e32 v2, v103, v2
	v_add_f32_e32 v2, v104, v2
	v_add_f32_e32 v6, v105, v2
	v_cvt_pk_bf16_f32 v170, v100, v101
	v_cvt_pk_bf16_f32 v171, v102, v103
	ds_read_b64_tr_b16 v[2:3], v0 offset:24576
	ds_read_b64_tr_b16 v[4:5], v0 offset:25088
	s_waitcnt lgkmcnt(3)
	v_mfma_f32_32x32x16_bf16 v[144:159], v[196:199], v[164:167], v[144:159]
	v_add_f32_e32 v6, v106, v6
	v_add_f32_e32 v6, v107, v6
	v_add_f32_e32 v6, v108, v6
	v_add_f32_e32 v10, v109, v6
	v_cvt_pk_bf16_f32 v160, v104, v105
	v_cvt_pk_bf16_f32 v161, v106, v107
	ds_read_b64_tr_b16 v[6:7], v0 offset:28672
	ds_read_b64_tr_b16 v[8:9], v0 offset:29184
	s_waitcnt lgkmcnt(4)
	v_mfma_f32_32x32x16_bf16 v[128:143], v[192:195], v[164:167], v[128:143]
	ds_read_b64_tr_b16 v[100:101], v0 offset:32768
	ds_read_b64_tr_b16 v[102:103], v0 offset:33280
	ds_read_b64_tr_b16 v[104:105], v0 offset:36864
	ds_read_b64_tr_b16 v[106:107], v0 offset:37376
	ds_read_b64_tr_b16 v[112:113], v0 offset:25600
	ds_read_b64_tr_b16 v[114:115], v0 offset:26112
	ds_read_b64_tr_b16 v[116:117], v0 offset:29696
	ds_read_b64_tr_b16 v[118:119], v0 offset:30208
	v_add_f32_e32 v10, v110, v10
	v_add_f32_e32 v10, v111, v10
	v_add_f32_e32 v12, 0, v10
	v_cvt_pk_bf16_f32 v162, v108, v109
	v_cvt_pk_bf16_f32 v163, v110, v111
	s_add_i32 m0, s78, s64
	v_lshl_add_u64 v[14:15], v[234:235], 0, s[6:7]
	v_lshl_add_u64 v[10:11], v[14:15], 0, s[56:57]
	v_lshl_add_u64 v[208:209], v[236:237], 0, s[6:7]
	global_load_lds_dwordx4 v[10:11], off
	s_lshl_b32 s72, s76, 1
	s_add_i32 m0, s72, s63
	v_lshl_add_u64 v[10:11], v[208:209], 0, s[48:49]
	v_lshl_add_u64 v[210:211], v[238:239], 0, s[6:7]
	global_load_lds_dwordx4 v[10:11], off
	s_addk_i32 m0, 0x2000
	v_lshl_add_u64 v[10:11], v[210:211], 0, s[48:49]
	global_load_lds_dwordx4 v[10:11], off
	v_max_f32_e32 v10, v145, v145
	v_max_f32_e32 v11, v144, v144
	v_max_f32_e32 v10, v11, v10
	v_max3_f32 v11, v146, v147, v129
	v_max3_f32 v10, v10, v128, v130
	v_max3_f32 v10, v10, v131, v148
	v_max3_f32 v11, v11, v150, v151
	v_max3_f32 v10, v10, v149, v132
	v_max3_f32 v11, v11, v134, v135
	v_max3_f32 v10, v10, v133, v152
	v_max3_f32 v11, v11, v154, v155
	v_max3_f32 v10, v10, v153, v136
	v_max3_f32 v11, v11, v138, v139
	v_max3_f32 v10, v10, v137, v156
	v_max3_f32 v11, v11, v158, v159
	v_max3_f32 v10, v10, v157, v140
	v_max3_f32 v11, v11, v142, v143
	v_max3_f32 v10, v10, v141, v11
	v_mov_b32_e32 v11, v10
	s_nop 1
	v_permlane32_swap_b32_e32 v10, v11
	v_max_f32_e32 v11, v11, v11
	v_max_f32_e32 v10, v10, v10
	v_max_f32_e32 v10, v10, v11
	v_cmp_lt_f32_e32 vcc, s96, v10
	s_cmp_lg_u64 vcc, 0
	v_add_f32_e32 v212, v231, v12
	s_cselect_b64 s[72:73], -1, 0
	s_cbranch_vccnz .LBB0_288

.LBB0_283:
	s_add_i32 s72, s76, 0x2000
	s_cmpk_lg_i32 s76, 0x4000
	s_cselect_b32 s87, s72, 0
	v_mfma_f32_32x32x16_bf16 v[112:127], v[96:99], v[184:187], v[80:95]
	v_add_f32_e32 v100, v144, v145
	v_add_f32_e32 v100, v146, v100
	v_add_f32_e32 v100, v147, v100
	s_lshl_b32 s72, s78, 1
	v_add_f32_e32 v100, v148, v100
	v_add_u32_e32 v233, s72, v245
	v_add_f32_e32 v96, v149, v100
	v_cvt_pk_bf16_f32 v188, v144, v145
	v_cvt_pk_bf16_f32 v189, v146, v147
	s_nop 0
	v_add_f32_e32 v96, v150, v96
	v_add_f32_e32 v96, v151, v96
	v_add_f32_e32 v96, v152, v96
	v_add_f32_e32 v144, v153, v96
	v_mfma_f32_32x32x16_bf16 v[96:111], v[10:13], v[184:187], v[80:95]
	v_cvt_pk_bf16_f32 v190, v148, v149
	v_cvt_pk_bf16_f32 v191, v150, v151
	v_mfma_f32_32x32x16_bf16 v[112:127], v[204:207], v[176:179], v[112:127]
	v_add_f32_e32 v10, v154, v144
	v_add_f32_e32 v10, v155, v10
	v_add_f32_e32 v10, v156, v10
	v_add_f32_e32 v10, v157, v10
	v_cvt_pk_bf16_f32 v180, v152, v153
	v_cvt_pk_bf16_f32 v181, v154, v155
	v_mfma_f32_32x32x16_bf16 v[96:111], v[192:195], v[176:179], v[96:111]
	v_add_f32_e32 v10, v158, v10
	v_add_f32_e32 v10, v159, v10
	v_add_f32_e32 v10, v128, v10
	v_add_f32_e32 v10, v129, v10
	v_cvt_pk_bf16_f32 v182, v156, v157
	v_cvt_pk_bf16_f32 v183, v158, v159
	v_mfma_f32_32x32x16_bf16 v[112:127], v[200:203], v[172:175], v[112:127]
	v_add_f32_e32 v10, v130, v10
	v_add_f32_e32 v10, v131, v10
	v_add_f32_e32 v10, v132, v10
	v_add_f32_e32 v10, v133, v10
	v_cvt_pk_bf16_f32 v168, v128, v129
	v_cvt_pk_bf16_f32 v169, v130, v131
	v_mfma_f32_32x32x16_bf16 v[96:111], v[6:9], v[172:175], v[96:111]
	v_add_f32_e32 v6, v134, v10
	v_add_f32_e32 v6, v135, v6
	v_add_f32_e32 v6, v136, v6
	v_add_f32_e32 v10, v137, v6
	v_cvt_pk_bf16_f32 v170, v132, v133
	v_cvt_pk_bf16_f32 v171, v134, v135
	ds_read_b64_tr_b16 v[6:7], v233 offset:24576
	ds_read_b64_tr_b16 v[8:9], v233 offset:25088
	v_mfma_f32_32x32x16_bf16 v[112:127], v[196:199], v[164:167], v[112:127]
	v_add_f32_e32 v10, v138, v10
	v_add_f32_e32 v10, v139, v10
	v_add_f32_e32 v10, v140, v10
	v_add_f32_e32 v128, v141, v10
	v_cvt_pk_bf16_f32 v160, v136, v137
	v_cvt_pk_bf16_f32 v161, v138, v139
	ds_read_b64_tr_b16 v[10:11], v233 offset:28672
	ds_read_b64_tr_b16 v[12:13], v233 offset:29184
	v_mfma_f32_32x32x16_bf16 v[96:111], v[2:5], v[164:167], v[96:111]
	ds_read_b64_tr_b16 v[144:145], v233 offset:32768
	ds_read_b64_tr_b16 v[146:147], v233 offset:33280
	ds_read_b64_tr_b16 v[148:149], v233 offset:36864
	ds_read_b64_tr_b16 v[150:151], v233 offset:37376
	ds_read_b64_tr_b16 v[152:153], v233 offset:25600
	ds_read_b64_tr_b16 v[154:155], v233 offset:26112
	ds_read_b64_tr_b16 v[156:157], v233 offset:29696
	ds_read_b64_tr_b16 v[158:159], v233 offset:30208
	v_add_f32_e32 v2, v142, v128
	v_add_f32_e32 v2, v143, v2
	v_add_f32_e32 v4, 0, v2
	v_cvt_pk_bf16_f32 v162, v140, v141
	v_cvt_pk_bf16_f32 v163, v142, v143
	s_add_i32 m0, s76, s64
	v_lshl_add_u64 v[2:3], v[14:15], 0, s[52:53]
	s_lshl_b32 s72, s87, 1
	global_load_lds_dwordx4 v[2:3], off
	s_add_i32 m0, s72, s63
	v_lshl_add_u64 v[2:3], v[208:209], 0, s[50:51]
	global_load_lds_dwordx4 v[2:3], off
	s_addk_i32 m0, 0x2000
	v_lshl_add_u64 v[2:3], v[210:211], 0, s[50:51]
	global_load_lds_dwordx4 v[2:3], off
	v_max_f32_e32 v2, v113, v113
	v_max_f32_e32 v3, v112, v112
	v_max_f32_e32 v2, v3, v2
	v_max3_f32 v3, v114, v115, v97
	v_max3_f32 v2, v2, v96, v98
	v_max3_f32 v2, v2, v99, v116
	v_max3_f32 v3, v3, v118, v119
	v_max3_f32 v2, v2, v117, v100
	v_max3_f32 v3, v3, v102, v103
	v_max3_f32 v2, v2, v101, v120
	v_max3_f32 v3, v3, v122, v123
	v_max3_f32 v2, v2, v121, v104
	v_max3_f32 v3, v3, v106, v107
	v_max3_f32 v2, v2, v105, v124
	v_max3_f32 v3, v3, v126, v127
	v_max3_f32 v2, v2, v125, v108
	v_max3_f32 v3, v3, v110, v111
	v_max3_f32 v2, v2, v109, v3
	v_mov_b32_e32 v3, v2
	s_nop 1
	v_permlane32_swap_b32_e32 v2, v3
	v_max_f32_e32 v3, v3, v3
	v_max_f32_e32 v2, v2, v2
	v_max_f32_e32 v2, v2, v3
	v_cmp_lt_f32_e32 vcc, s96, v2
	s_cmp_lg_u64 vcc, 0
	v_add_f32_e32 v231, v212, v4
	s_cselect_b64 s[72:73], -1, 0
	s_cbranch_vccnz .LBB0_291
